# v30: v26 + P2 per-head sum-of-squares butterflies via DPP (quad_perm/row_half_mirror/row_mirror) instead of ds_bpermute; bitwise same f32 sums
# baseline (speedup 1.0000x reference)
; __device__ __forceinline__ float bf2f(unsigned b) { return __uint_as_float(b << 16); }
; __device__ __forceinline__ unsigned pk2(float lo, float hi) { f32x2_t v = {lo, hi}; bf16x2_t b = __builtin_convertvector(v, bf16x2_t); return __builtin_bit_cast(unsigned, b); }
; __global__ void __launch_bounds__(512, 2) mega_fwd(Args args) {
;     ...
;                 float cs[4], sn[4];
; #pragma unroll
;                 for (int e = 0; e < 4; ++e) { const double t = (double)pos * INVF[sub * 4 + e] * 0.15915494309189535; const float fr = (float)(t - rint(t));
;                     cs[e] = __builtin_amdgcn_cosf(fr); sn[e] = __builtin_amdgcn_sinf(fr); }
;                 const bf16_t* pr = PROJ + (size_t)row * INW;
; #pragma unroll
;                 for (int p = 0; p < 4; ++p) { const int hh = p * 4 + hq;
;                     const u32x2 a1 = ra[2 * p], a2 = ra[2 * p + 1];
;                     float x1[4] = {bf2f(a1.x & 0xffffu), bf2f(a1.x >> 16), bf2f(a1.y & 0xffffu), bf2f(a1.y >> 16)};
;                     float x2[4] = {bf2f(a2.x & 0xffffu), bf2f(a2.x >> 16), bf2f(a2.y & 0xffffu), bf2f(a2.y >> 16)};
;                     float ss = (x1[0] * x1[0] + x1[1] * x1[1]) + (x1[2] * x1[2] + x1[3] * x1[3]) + (x2[0] * x2[0] + x2[1] * x2[1]) + (x2[2] * x2[2] + x2[3] * x2[3]);
;                     ss += __shfl_xor(ss, 1); ss += __shfl_xor(ss, 2); ss += __shfl_xor(ss, 4); ss += __shfl_xor(ss, 8);
;                     const float rstd = rsqrtf(ss * (1.f / HD) + EPS);
;                     const float* gp = hh < 8 ? q_norm : k_norm; const f32x4 g1 = *(const f32x4*)(gp + sub * 4), g2 = *(const f32x4*)(gp + 64 + sub * 4);
;                     float o1[4], o2[4];
; #pragma unroll
;                     for (int e = 0; e < 4; ++e) { const float y1 = x1[e] * rstd * g1[e], y2 = x2[e] * rstd * g2[e]; o1[e] = y1 * cs[e] - y2 * sn[e]; o2[e] = y1 * sn[e] + y2 * cs[e]; }
;                     bf16_t* dst = (hh < 8 ? QN : KN) + (size_t)row * 1024 + (hh & 7) * 128 + sub * 4;
;                     u32x2 w1, w2; w1.x = pk2(o1[0], o1[1]); w1.y = pk2(o1[2], o1[3]); w2.x = pk2(o2[0], o2[1]); w2.y = pk2(o2[2], o2[3]);
;                     *(u32x2*)dst = w1; *(u32x2*)(dst + 64) = w2;
.LBB0_171:
	global_load_dwordx4 v[72:75], v[22:23], off
	global_load_dwordx4 v[76:79], v[22:23], off offset:256
	v_and_b32_e32 v67, 0xffff0000, v61
	v_and_b32_e32 v83, 0xffff0000, v60
	v_lshlrev_b32_e32 v66, 16, v61
	v_and_b32_e32 v81, 0xffff0000, v59
	v_lshlrev_b32_e32 v82, 16, v60
	v_and_b32_e32 v85, 0xffff0000, v58
	v_mov_b32_e32 v60, v83
	v_mov_b32_e32 v61, v67
	v_lshlrev_b32_e32 v80, 16, v59
	v_lshlrev_b32_e32 v84, 16, v58
	v_mov_b32_e32 v58, v82
	v_mov_b32_e32 v59, v66
	v_mov_b32_e32 v64, v81
	v_mov_b32_e32 v65, v85
	v_pk_mul_f32 v[60:61], v[60:61], v[60:61]
	v_mov_b32_e32 v62, v80
	v_mov_b32_e32 v63, v84
	v_pk_mul_f32 v[64:65], v[64:65], v[64:65]
	v_pk_fma_f32 v[58:59], v[58:59], v[58:59], v[60:61]
	v_pk_fma_f32 v[60:61], v[62:63], v[62:63], v[64:65]
	v_add_f32_e32 v37, v58, v59
	v_add_f32_e32 v37, v37, v61
	v_add_f32_e32 v37, v60, v37
	s_cmpk_lt_i32 s4, 0x4000
	s_cselect_b64 s[30:31], -1, 0
	s_and_b64 s[44:45], s[30:31], exec
	s_cselect_b32 s5, s4, s23
	s_waitcnt lgkmcnt(0)
	v_add_f32_dpp v37, v37, v37 quad_perm:[1,0,3,2] row_mask:0xf bank_mask:0xf
	v_cvt_f64_i32_e32 v[62:63], s5
	v_mul_f64 v[58:59], v[4:5], v[62:63]
	v_mul_f64 v[64:65], v[6:7], v[62:63]
	v_mul_f64 v[86:87], v[0:1], v[62:63]
	s_waitcnt lgkmcnt(0)
	v_add_f32_dpp v37, v37, v37 quad_perm:[2,3,0,1] row_mask:0xf bank_mask:0xf
	v_mul_f64 v[62:63], v[2:3], v[62:63]
	v_mul_f64 v[88:89], v[58:59], s[20:21]
	v_mul_f64 v[90:91], v[64:65], s[20:21]
	v_mul_f64 v[94:95], v[86:87], s[20:21]
	v_mul_f64 v[96:97], v[62:63], s[20:21]
	v_rndne_f64_e32 v[60:61], v[88:89]
	v_rndne_f64_e32 v[88:89], v[90:91]
	v_rndne_f64_e32 v[90:91], v[94:95]
	v_rndne_f64_e32 v[94:95], v[96:97]
	v_fma_f64 v[58:59], v[58:59], s[20:21], -v[60:61]
	v_fma_f64 v[60:61], v[64:65], s[20:21], -v[88:89]
	v_fma_f64 v[64:65], v[86:87], s[20:21], -v[90:91]
	v_fma_f64 v[62:63], v[62:63], s[20:21], -v[94:95]
	s_waitcnt lgkmcnt(0)
	v_add_f32_dpp v37, v37, v37 row_half_mirror row_mask:0xf bank_mask:0xf
	v_cvt_f32_f64_e32 v64, v[64:65]
	v_cvt_f32_f64_e32 v65, v[62:63]
	v_cvt_f32_f64_e32 v59, v[58:59]
	v_cvt_f32_f64_e32 v61, v[60:61]
	v_cos_f32_e32 v58, v59
	v_sin_f32_e32 v60, v59
	s_waitcnt lgkmcnt(0)
	v_add_f32_dpp v37, v37, v37 row_mirror row_mask:0xf bank_mask:0xf
	v_fmamk_f32 v37, v37, 0x3c000000, v34
	v_mul_f32_e32 v63, 0x4b800000, v37
	v_cmp_gt_f32_e32 vcc, s13, v37
	v_cos_f32_e32 v59, v61
	v_sin_f32_e32 v61, v61
	v_cndmask_b32_e32 v37, v37, v63, vcc
	v_rsq_f32_e32 v37, v37
	v_cos_f32_e32 v62, v64
	v_sin_f32_e32 v64, v64
	v_cos_f32_e32 v63, v65
	v_mul_f32_e32 v71, 0x45800000, v37
	v_cndmask_b32_e32 v86, v37, v71, vcc
	v_pk_mul_f32 v[84:85], v[86:87], v[84:85] op_sel_hi:[0,1]
	v_sin_f32_e32 v65, v65
	v_pk_mul_f32 v[82:83], v[86:87], v[82:83] op_sel_hi:[0,1]
	v_pk_mul_f32 v[66:67], v[86:87], v[66:67] op_sel_hi:[0,1]
	v_and_b32_e32 v97, 0xffff0000, v11
	v_and_b32_e32 v95, 0xffff0000, v8
	v_lshlrev_b32_e32 v96, 16, v11
	v_and_b32_e32 v99, 0xffff0000, v9
	s_waitcnt vmcnt(1)
	v_pk_mul_f32 v[72:73], v[72:73], v[82:83]
	s_waitcnt vmcnt(0)
	v_pk_mul_f32 v[76:77], v[76:77], v[84:85]
	v_pk_mul_f32 v[66:67], v[74:75], v[66:67]
	v_pk_mul_f32 v[74:75], v[76:77], v[60:61]
	v_pk_mul_f32 v[76:77], v[58:59], v[76:77]
	v_pk_fma_f32 v[74:75], v[72:73], v[58:59], v[74:75] neg_lo:[0,0,1] neg_hi:[0,0,1]
	v_pk_fma_f32 v[72:73], v[72:73], v[60:61], v[76:77]
	v_pk_mul_f32 v[76:77], v[86:87], v[80:81] op_sel_hi:[0,1]
	v_pk_mul_f32 v[76:77], v[78:79], v[76:77]
	v_lshl_add_u64 v[80:81], v[30:31], 0, v[18:19]
	v_pk_mul_f32 v[78:79], v[76:77], v[64:65]
	v_pk_mul_f32 v[76:77], v[62:63], v[76:77]
	v_pk_fma_f32 v[78:79], v[66:67], v[62:63], v[78:79] neg_lo:[0,0,1] neg_hi:[0,0,1]
	v_pk_fma_f32 v[66:67], v[66:67], v[64:65], v[76:77]
	v_cvt_pk_bf16_f32 v72, v72, v73
	v_cvt_pk_bf16_f32 v73, v66, v67
	v_add_co_u32_e32 v66, vcc, s15, v80
	v_cvt_pk_bf16_f32 v74, v74, v75
	v_cvt_pk_bf16_f32 v75, v78, v79
	v_addc_co_u32_e32 v67, vcc, 0, v81, vcc
	global_store_dwordx2 v[66:67], v[74:75], off
	global_store_dwordx2 v[66:67], v[72:73], off offset:128
	global_load_dwordx4 v[72:75], v[22:23], off offset:256
	s_nop 0
	global_load_dwordx4 v[76:79], v[22:23], off
	v_and_b32_e32 v83, 0xffff0000, v15
	v_and_b32_e32 v87, 0xffff0000, v14
	v_lshlrev_b32_e32 v82, 16, v15
	v_and_b32_e32 v85, 0xffff0000, v13
	v_lshlrev_b32_e32 v86, 16, v14
	v_and_b32_e32 v15, 0xffff0000, v12
	v_mov_b32_e32 v88, v87
	v_mov_b32_e32 v89, v83
	v_lshlrev_b32_e32 v84, 16, v13
	v_lshlrev_b32_e32 v14, 16, v12
	v_mov_b32_e32 v12, v86
	v_mov_b32_e32 v13, v82
	v_pk_mul_f32 v[88:89], v[88:89], v[88:89]
	v_mov_b32_e32 v90, v85
	v_mov_b32_e32 v91, v15
	v_pk_fma_f32 v[12:13], v[12:13], v[12:13], v[88:89]
	v_mov_b32_e32 v88, v84
	v_mov_b32_e32 v89, v14
	v_pk_mul_f32 v[90:91], v[90:91], v[90:91]
	v_mov_b32_e32 v11, v97
	v_pk_fma_f32 v[88:89], v[88:89], v[88:89], v[90:91]
	v_and_b32_e32 v91, 0xffff0000, v10
	v_lshlrev_b32_e32 v90, 16, v10
	v_mov_b32_e32 v10, v91
	v_lshlrev_b32_e32 v94, 16, v8
	v_lshlrev_b32_e32 v98, 16, v9
	v_mov_b32_e32 v8, v90
	v_mov_b32_e32 v9, v96
	v_pk_mul_f32 v[10:11], v[10:11], v[10:11]
	v_mov_b32_e32 v100, v99
	v_mov_b32_e32 v101, v95
	v_pk_fma_f32 v[8:9], v[8:9], v[8:9], v[10:11]
	v_mov_b32_e32 v10, v98
	v_mov_b32_e32 v11, v94
	v_pk_mul_f32 v[100:101], v[100:101], v[100:101]
	s_cmpk_gt_i32 s4, 0x37ff
	v_pk_fma_f32 v[10:11], v[10:11], v[10:11], v[100:101]
	v_mov_b32_e32 v100, v8
	v_mov_b32_e32 v101, v12
	v_mov_b32_e32 v12, v9
	v_pk_add_f32 v[8:9], v[100:101], v[12:13]
	v_mov_b32_e32 v12, v11
	v_mov_b32_e32 v13, v89
	v_pk_add_f32 v[8:9], v[8:9], v[12:13]
	v_mov_b32_e32 v11, v88
	v_pk_add_f32 v[8:9], v[10:11], v[8:9]
	s_cselect_b64 s[48:49], -1, 0
	s_add_i32 s10, s4, 0xffffc000
	s_lshl_b64 s[44:45], s[10:11], 12
	s_add_i32 s10, s4, 0xffffc800
	s_waitcnt lgkmcnt(0)
; __device__ __forceinline__ unsigned pk2(float lo, float hi) { f32x2_t v = {lo, hi}; bf16x2_t b = __builtin_convertvector(v, bf16x2_t); return __builtin_bit_cast(unsigned, b); }
; __global__ void __launch_bounds__(512, 2) mega_fwd(Args args) {
;     ...
;                     ss += __shfl_xor(ss, 1); ss += __shfl_xor(ss, 2); ss += __shfl_xor(ss, 4); ss += __shfl_xor(ss, 8);
;                     const float rstd = rsqrtf(ss * (1.f / HD) + EPS);
;                     const float* gp = hh < 8 ? q_norm : k_norm; const f32x4 g1 = *(const f32x4*)(gp + sub * 4), g2 = *(const f32x4*)(gp + 64 + sub * 4);
;                     float o1[4], o2[4];
; #pragma unroll
;                     for (int e = 0; e < 4; ++e) { const float y1 = x1[e] * rstd * g1[e], y2 = x2[e] * rstd * g2[e]; o1[e] = y1 * cs[e] - y2 * sn[e]; o2[e] = y1 * sn[e] + y2 * cs[e]; }
;                     bf16_t* dst = (hh < 8 ? QN : KN) + (size_t)row * 1024 + (hh & 7) * 128 + sub * 4;
;                     u32x2 w1, w2; w1.x = pk2(o1[0], o1[1]); w1.y = pk2(o1[2], o1[3]); w2.x = pk2(o2[0], o2[1]); w2.y = pk2(o2[2], o2[3]);
;                     *(u32x2*)dst = w1; *(u32x2*)(dst + 64) = w2;
;                     if (hh >= 8 && row >= T - 2048) { float* ko = (row < T ? out + O_PWK + (size_t)(row - (T - 2048)) * 1024 : out + O_SWK + (size_t)(row - T) * 1024) + (hh - 8) * 128 + sub * 4;
;                         *(f32x4*)ko = (f32x4){o1[0], o1[1], o1[2], o1[3]}; *(f32x4*)(ko + 64) = (f32x4){o2[0], o2[1], o2[2], o2[3]}; } }
	v_add_f32_dpp v8, v8, v8 quad_perm:[1,0,3,2] row_mask:0xf bank_mask:0xf
	v_add_f32_dpp v9, v9, v9 quad_perm:[1,0,3,2] row_mask:0xf bank_mask:0xf
	s_lshl_b64 s[46:47], s[10:11], 12
	s_cmpk_lt_i32 s4, 0x3800
	s_waitcnt lgkmcnt(0)
	v_add_f32_dpp v8, v8, v8 quad_perm:[2,3,0,1] row_mask:0xf bank_mask:0xf
	v_add_f32_dpp v9, v9, v9 quad_perm:[2,3,0,1] row_mask:0xf bank_mask:0xf
	s_waitcnt lgkmcnt(0)
	v_add_f32_dpp v8, v8, v8 row_half_mirror row_mask:0xf bank_mask:0xf
	v_add_f32_dpp v9, v9, v9 row_half_mirror row_mask:0xf bank_mask:0xf
	s_waitcnt lgkmcnt(0)
	v_add_f32_dpp v8, v8, v8 row_mirror row_mask:0xf bank_mask:0xf
	v_add_f32_dpp v9, v9, v9 row_mirror row_mask:0xf bank_mask:0xf
	s_nop 0
	v_pk_fma_f32 v[88:89], v[8:9], s[22:23], v[34:35] op_sel_hi:[1,0,0]
	s_nop 0
	v_mul_f32_e32 v8, 0x4b800000, v89
	v_cmp_gt_f32_e32 vcc, s13, v89
	v_mul_f32_e32 v37, 0x4b800000, v88
	s_nop 0
	v_cndmask_b32_e32 v8, v89, v8, vcc
	v_rsq_f32_e32 v8, v8
	s_nop 0
	v_mul_f32_e32 v9, 0x45800000, v8
	v_cndmask_b32_e32 v8, v8, v9, vcc
	v_pk_mul_f32 v[12:13], v[8:9], v[14:15] op_sel_hi:[0,1]
	v_pk_mul_f32 v[10:11], v[8:9], v[86:87] op_sel_hi:[0,1]
	s_waitcnt vmcnt(1)
	v_pk_mul_f32 v[12:13], v[72:73], v[12:13]
	s_waitcnt vmcnt(0)
	v_pk_mul_f32 v[10:11], v[76:77], v[10:11]
	v_pk_mul_f32 v[14:15], v[12:13], v[60:61]
	v_pk_mul_f32 v[12:13], v[58:59], v[12:13]
	v_pk_fma_f32 v[14:15], v[10:11], v[58:59], v[14:15] neg_lo:[0,0,1] neg_hi:[0,0,1]
	v_pk_fma_f32 v[10:11], v[10:11], v[60:61], v[12:13]
	v_pk_mul_f32 v[12:13], v[8:9], v[82:83] op_sel_hi:[0,1]
	v_pk_mul_f32 v[8:9], v[8:9], v[84:85] op_sel_hi:[0,1]
	v_pk_mul_f32 v[8:9], v[74:75], v[8:9]
	v_pk_mul_f32 v[12:13], v[78:79], v[12:13]
	v_pk_mul_f32 v[72:73], v[8:9], v[64:65]
	v_pk_mul_f32 v[8:9], v[62:63], v[8:9]
	v_pk_fma_f32 v[72:73], v[12:13], v[62:63], v[72:73] neg_lo:[0,0,1] neg_hi:[0,0,1]
	v_pk_fma_f32 v[8:9], v[12:13], v[64:65], v[8:9]
	v_cvt_pk_bf16_f32 v12, v14, v15
	v_cvt_pk_bf16_f32 v13, v72, v73
	v_cvt_pk_bf16_f32 v10, v10, v11
	v_cvt_pk_bf16_f32 v11, v8, v9
	global_store_dwordx2 v[66:67], v[12:13], off offset:1024
	global_store_dwordx2 v[66:67], v[10:11], off offset:1152
	global_load_dwordx4 v[8:11], v[24:25], off
	s_nop 0
	global_load_dwordx4 v[12:15], v[24:25], off offset:256
	v_add_co_u32_e32 v66, vcc, 0x20000000, v80
	s_nop 1
	v_addc_co_u32_e32 v67, vcc, 0, v81, vcc
	s_nop 1
	v_cmp_gt_f32_e32 vcc, s13, v88
	s_nop 1
	v_cndmask_b32_e32 v37, v88, v37, vcc
	v_rsq_f32_e32 v37, v37
	s_nop 0
	v_mul_f32_e32 v71, 0x45800000, v37
	v_cndmask_b32_e32 v72, v37, v71, vcc
	v_pk_mul_f32 v[74:75], v[72:73], v[90:91] op_sel_hi:[0,1]
	v_pk_mul_f32 v[76:77], v[72:73], v[94:95] op_sel_hi:[0,1]
	v_pk_mul_f32 v[78:79], v[72:73], v[96:97] op_sel_hi:[0,1]
	v_pk_mul_f32 v[72:73], v[72:73], v[98:99] op_sel_hi:[0,1]
	s_waitcnt vmcnt(1)
	v_pk_mul_f32 v[8:9], v[8:9], v[74:75]
	s_waitcnt vmcnt(0)
	v_pk_mul_f32 v[12:13], v[12:13], v[76:77]
	v_pk_mul_f32 v[14:15], v[14:15], v[72:73]
	v_pk_mul_f32 v[10:11], v[10:11], v[78:79]
	v_pk_mul_f32 v[72:73], v[12:13], v[60:61]
	v_pk_mul_f32 v[76:77], v[14:15], v[64:65]
	v_pk_mul_f32 v[74:75], v[58:59], v[12:13]
	v_pk_mul_f32 v[78:79], v[62:63], v[14:15]
	v_pk_fma_f32 v[12:13], v[8:9], v[58:59], v[72:73] neg_lo:[0,0,1] neg_hi:[0,0,1]
	v_pk_fma_f32 v[14:15], v[10:11], v[62:63], v[76:77] neg_lo:[0,0,1] neg_hi:[0,0,1]
	v_pk_fma_f32 v[8:9], v[8:9], v[60:61], v[74:75]
	v_pk_fma_f32 v[10:11], v[10:11], v[64:65], v[78:79]
	v_cvt_pk_bf16_f32 v72, v12, v13
	v_cvt_pk_bf16_f32 v73, v14, v15
	v_cvt_pk_bf16_f32 v74, v8, v9
	v_cvt_pk_bf16_f32 v75, v10, v11
	global_store_dwordx2 v[66:67], v[72:73], off
	global_store_dwordx2 v[66:67], v[74:75], off offset:128
	v_lshlrev_b32_e32 v66, 2, v20
	s_cbranch_scc1 .LBB0_173
	s_load_dwordx2 s[4:5], s[8:9], 0xf0
	s_and_b64 s[50:51], s[30:31], exec
	s_cselect_b32 s10, s27, 0x93fa000
	s_cselect_b32 s16, s47, s45
	s_cselect_b32 s17, s46, s44
	s_waitcnt lgkmcnt(0)
	s_add_u32 s4, s4, s10
	s_addc_u32 s5, s5, 0
	s_add_u32 s4, s4, s17
	s_addc_u32 s5, s5, s16
	v_lshl_add_u64 v[72:73], s[4:5], 0, v[16:17]
	v_mov_b32_e32 v67, v17
	v_lshl_add_u64 v[72:73], v[72:73], 0, v[66:67]
	global_store_dwordx4 v[72:73], v[12:15], off
	global_store_dwordx4 v[72:73], v[8:11], off offset:256
; __global__ void __launch_bounds__(512, 2) mega_fwd(Args args) {
;     ...
;                 for (int p = 0; p < 4; ++p) { const int hh = p * 4 + hq;
;                     const u32x2 a1 = ra[2 * p], a2 = ra[2 * p + 1];
;                     float x1[4] = {bf2f(a1.x & 0xffffu), bf2f(a1.x >> 16), bf2f(a1.y & 0xffffu), bf2f(a1.y >> 16)};
;                     float x2[4] = {bf2f(a2.x & 0xffffu), bf2f(a2.x >> 16), bf2f(a2.y & 0xffffu), bf2f(a2.y >> 16)};
;                     float ss = (x1[0] * x1[0] + x1[1] * x1[1]) + (x1[2] * x1[2] + x1[3] * x1[3]) + (x2[0] * x2[0] + x2[1] * x2[1]) + (x2[2] * x2[2] + x2[3] * x2[3]);
;                     ss += __shfl_xor(ss, 1); ss += __shfl_xor(ss, 2); ss += __shfl_xor(ss, 4); ss += __shfl_xor(ss, 8);
;                     const float rstd = rsqrtf(ss * (1.f / HD) + EPS);
;                     const float* gp = hh < 8 ? q_norm : k_norm; const f32x4 g1 = *(const f32x4*)(gp + sub * 4), g2 = *(const f32x4*)(gp + 64 + sub * 4);
;                     float o1[4], o2[4];
; #pragma unroll
;                     for (int e = 0; e < 4; ++e) { const float y1 = x1[e] * rstd * g1[e], y2 = x2[e] * rstd * g2[e]; o1[e] = y1 * cs[e] - y2 * sn[e]; o2[e] = y1 * sn[e] + y2 * cs[e]; }
;                     bf16_t* dst = (hh < 8 ? QN : KN) + (size_t)row * 1024 + (hh & 7) * 128 + sub * 4;
;                     u32x2 w1, w2; w1.x = pk2(o1[0], o1[1]); w1.y = pk2(o1[2], o1[3]); w2.x = pk2(o2[0], o2[1]); w2.y = pk2(o2[2], o2[3]);
;                     *(u32x2*)dst = w1; *(u32x2*)(dst + 64) = w2;
;                     if (hh >= 8 && row >= T - 2048) { float* ko = (row < T ? out + O_PWK + (size_t)(row - (T - 2048)) * 1024 : out + O_SWK + (size_t)(row - T) * 1024) + (hh - 8) * 128 + sub * 4;
;                         *(f32x4*)ko = (f32x4){o1[0], o1[1], o1[2], o1[3]}; *(f32x4*)(ko + 64) = (f32x4){o2[0], o2[1], o2[2], o2[3]}; } }
;                 if (row >= T - 2048) { float* vo = row < T ? out + O_PWV + (size_t)(row - (T - 2048)) * 1024 : out + O_SWV + (size_t)(row - T) * 1024;
; #pragma unroll
;                     for (int j = 0; j < 2; ++j) { float f[8]; unpack8(*(const u32x4*)(pr + 3072 + lane * 8 + 512 * j), f);
;                         *(f32x4*)(vo + lane * 8 + 512 * j) = (f32x4){f[0], f[1], f[2], f[3]}; *(f32x4*)(vo + lane * 8 + 512 * j + 4) = (f32x4){f[4], f[5], f[6], f[7]}; } }
.LBB0_173:
	s_nop 0
	global_load_dwordx4 v[8:11], v[24:25], off
	s_nop 0
	global_load_dwordx4 v[12:15], v[24:25], off offset:256
	v_lshlrev_b32_e32 v72, 16, v56
	v_and_b32_e32 v73, 0xffff0000, v56
	v_lshlrev_b32_e32 v56, 16, v57
	v_and_b32_e32 v57, 0xffff0000, v57
	v_lshlrev_b32_e32 v74, 16, v54
	v_and_b32_e32 v75, 0xffff0000, v54
	v_lshlrev_b32_e32 v54, 16, v55
	v_and_b32_e32 v55, 0xffff0000, v55
	v_mov_b32_e32 v78, v73
	v_mov_b32_e32 v79, v57
	v_mov_b32_e32 v76, v72
	v_mov_b32_e32 v77, v56
	v_mov_b32_e32 v82, v55
	v_mov_b32_e32 v83, v75
	v_pk_mul_f32 v[78:79], v[78:79], v[78:79]
	v_mov_b32_e32 v80, v54
	v_mov_b32_e32 v81, v74
	v_pk_mul_f32 v[82:83], v[82:83], v[82:83]
	v_pk_fma_f32 v[76:77], v[76:77], v[76:77], v[78:79]
	v_pk_fma_f32 v[78:79], v[80:81], v[80:81], v[82:83]
	v_add_f32_e32 v37, v76, v77
	v_add_f32_e32 v37, v37, v79
	v_add_f32_e32 v37, v78, v37
	v_lshl_add_u64 v[76:77], v[28:29], 0, v[18:19]
	v_add_co_u32_e32 v76, vcc, 0x20000000, v76
	s_waitcnt lgkmcnt(0)
	v_add_f32_dpp v37, v37, v37 quad_perm:[1,0,3,2] row_mask:0xf bank_mask:0xf
	v_addc_co_u32_e32 v77, vcc, 0, v77, vcc
	s_andn2_b64 vcc, exec, s[48:49]
	s_waitcnt lgkmcnt(0)
	v_add_f32_dpp v37, v37, v37 quad_perm:[2,3,0,1] row_mask:0xf bank_mask:0xf
	s_waitcnt lgkmcnt(0)
	s_nop 0
	v_add_f32_dpp v37, v37, v37 row_half_mirror row_mask:0xf bank_mask:0xf
	s_waitcnt lgkmcnt(0)
	s_nop 0
	v_add_f32_dpp v37, v37, v37 row_mirror row_mask:0xf bank_mask:0xf
	v_fmamk_f32 v37, v37, 0x3c000000, v34
	v_mul_f32_e32 v67, 0x4b800000, v37
	v_cmp_gt_f32_e64 s[4:5], s13, v37
	s_nop 1
	v_cndmask_b32_e64 v37, v37, v67, s[4:5]
	v_rsq_f32_e32 v37, v37
	s_nop 0
	v_mul_f32_e32 v67, 0x45800000, v37
	v_cndmask_b32_e64 v78, v37, v67, s[4:5]
	v_pk_mul_f32 v[74:75], v[78:79], v[74:75] op_sel_hi:[0,1]
	v_pk_mul_f32 v[54:55], v[78:79], v[54:55] op_sel_hi:[0,1]
	v_pk_mul_f32 v[72:73], v[78:79], v[72:73] op_sel_hi:[0,1]
	v_pk_mul_f32 v[56:57], v[78:79], v[56:57] op_sel_hi:[0,1]
	s_waitcnt vmcnt(1)
	v_pk_mul_f32 v[8:9], v[8:9], v[72:73]
	s_waitcnt vmcnt(0)
	v_pk_mul_f32 v[12:13], v[12:13], v[74:75]
	v_pk_mul_f32 v[14:15], v[14:15], v[54:55]
	v_pk_mul_f32 v[10:11], v[10:11], v[56:57]
	v_pk_mul_f32 v[54:55], v[12:13], v[60:61]
	v_pk_mul_f32 v[72:73], v[14:15], v[64:65]
	v_pk_mul_f32 v[56:57], v[58:59], v[12:13]
	v_pk_mul_f32 v[74:75], v[62:63], v[14:15]
	v_pk_fma_f32 v[12:13], v[8:9], v[58:59], v[54:55] neg_lo:[0,0,1] neg_hi:[0,0,1]
	v_pk_fma_f32 v[14:15], v[10:11], v[62:63], v[72:73] neg_lo:[0,0,1] neg_hi:[0,0,1]
	v_pk_fma_f32 v[8:9], v[8:9], v[60:61], v[56:57]
	v_pk_fma_f32 v[10:11], v[10:11], v[64:65], v[74:75]
	v_cvt_pk_bf16_f32 v54, v12, v13
	v_cvt_pk_bf16_f32 v55, v14, v15
	v_cvt_pk_bf16_f32 v56, v8, v9
	v_cvt_pk_bf16_f32 v57, v10, v11
	global_store_dwordx2 v[76:77], v[54:55], off
	global_store_dwordx2 v[76:77], v[56:57], off offset:128
	s_cbranch_vccnz .LBB0_168
	s_load_dwordx2 s[4:5], s[8:9], 0xf0
	s_and_b64 s[48:49], s[30:31], exec
	s_cselect_b32 s10, s27, 0x93fa000
	s_cselect_b32 s16, s47, s45
	s_cselect_b32 s17, s46, s44
	s_waitcnt lgkmcnt(0)
	s_add_u32 s10, s4, s10
	s_addc_u32 s35, s5, 0
	s_add_u32 s44, s10, s17
	s_addc_u32 s45, s35, s16
	v_mov_b32_e32 v37, v17
	v_lshl_add_u64 v[54:55], s[44:45], 0, v[36:37]
	v_mov_b32_e32 v67, v17
	v_lshl_add_u64 v[54:55], v[54:55], 0, v[66:67]
	global_store_dwordx4 v[54:55], v[12:15], off offset:-4096
	global_store_dwordx4 v[54:55], v[8:11], off offset:-3840
	s_nop 0
	global_load_dwordx4 v[8:11], v[26:27], off offset:-1024
	s_and_b64 s[30:31], s[30:31], exec
	s_cselect_b32 s10, s33, 0x947a000
	s_add_u32 s4, s4, s10
	s_addc_u32 s5, s5, 0
	s_add_u32 s4, s4, s17
	s_addc_u32 s5, s5, s16
	s_waitcnt vmcnt(0)
	v_lshlrev_b32_e32 v12, 16, v8
	v_and_b32_e32 v13, 0xffff0000, v8
	v_lshlrev_b32_e32 v14, 16, v9
	v_and_b32_e32 v15, 0xffff0000, v9
	v_lshlrev_b32_e32 v8, 16, v10
	v_and_b32_e32 v9, 0xffff0000, v10
	v_lshlrev_b32_e32 v10, 16, v11
	v_and_b32_e32 v11, 0xffff0000, v11
	global_store_dwordx4 v70, v[12:15], s[4:5]
	global_store_dwordx4 v70, v[8:11], s[4:5] offset:16
	s_nop 0
	global_load_dwordx4 v[8:11], v[26:27], off
	s_waitcnt vmcnt(0)
	v_lshlrev_b32_e32 v12, 16, v8
	v_and_b32_e32 v13, 0xffff0000, v8
	v_lshlrev_b32_e32 v14, 16, v9
	v_and_b32_e32 v15, 0xffff0000, v9
	v_lshlrev_b32_e32 v8, 16, v10
	v_and_b32_e32 v9, 0xffff0000, v10
	v_lshlrev_b32_e32 v10, 16, v11
	v_and_b32_e32 v11, 0xffff0000, v11
	global_store_dwordx4 v70, v[12:15], s[4:5] offset:2048
	global_store_dwordx4 v70, v[8:11], s[4:5] offset:2064
	s_branch .LBB0_168

; __device__ __forceinline__ u32x4 pack8(const float* f) { u32x4 o; o.x = pk2(f[0], f[1]); o.y = pk2(f[2], f[3]); o.z = pk2(f[4], f[5]); o.w = pk2(f[6], f[7]); return o; }
; __global__ void __launch_bounds__(512, 2) mega_fwd(Args args) {
;     ...
;         for (int row = gw; row < NMEM; row += NGW) {
;             const float* kp = MEMKV + (size_t)row * 1024 + lane * 8; const f32x4 a = *(const f32x4*)kp, b = *(const f32x4*)(kp + 4);
;             float f[8] = {a.x, a.y, a.z, a.w, b.x, b.y, b.z, b.w}; float ss = 0.f;
; #pragma unroll
;             for (int e = 0; e < 8; ++e) ss += f[e] * f[e];
;             ss += __shfl_xor(ss, 1); ss += __shfl_xor(ss, 2); ss += __shfl_xor(ss, 4); ss += __shfl_xor(ss, 8);
;             const float rstd = rsqrtf(ss * (1.f / HD) + EPS);
; #pragma unroll
;             for (int e = 0; e < 8; ++e) f[e] = f[e] * rstd * mem_k_norm[(lane & 15) * 8 + e];
;             float* ko = out + O_PMK + (size_t)row * 512 + lane * 8; *(f32x4*)ko = (f32x4){f[0], f[1], f[2], f[3]}; *(f32x4*)(ko + 4) = (f32x4){f[4], f[5], f[6], f[7]};
;             *(u32x4*)(MK + (size_t)row * 512 + lane * 8) = pack8(f);
;             const float* vp = kp + 512; const f32x4 c = *(const f32x4*)vp, dd = *(const f32x4*)(vp + 4);
;             float* vo = out + O_PMV + (size_t)row * 512 + lane * 8; *(f32x4*)vo = c; *(f32x4*)(vo + 4) = dd;
;             float fv[8] = {c.x, c.y, c.z, c.w, dd.x, dd.y, dd.z, dd.w}; *(u32x4*)(MV + (size_t)row * 512 + lane * 8) = pack8(fv);
;         }
.LBB0_335:
	v_lshl_add_u64 v[26:27], s[10:11], 0, v[92:93]
	v_add_co_u32_e32 v30, vcc, 0x6500000, v26
	v_lshl_add_u64 v[28:29], v[26:27], 0, s[20:21]
	s_nop 0
	v_addc_co_u32_e32 v31, vcc, 0, v27, vcc
	global_load_dwordx4 v[10:13], v[30:31], off
	global_load_dwordx4 v[14:17], v[28:29], off offset:16
	global_load_dwordx4 v[18:21], v[0:1], off
	global_load_dwordx4 v[22:25], v[0:1], off offset:16
	v_add_co_u32_e32 v32, vcc, s27, v2
	v_lshl_add_u64 v[28:29], s[6:7], 0, v[92:93]
	s_nop 0
	v_addc_co_u32_e32 v33, vcc, -1, v3, vcc
	v_add_co_u32_e32 v34, vcc, s15, v28
	v_lshl_add_u64 v[26:27], v[26:27], 0, s[22:23]
	s_nop 0
	v_addc_co_u32_e32 v35, vcc, 0, v29, vcc
	s_add_i32 s29, s29, s14
	s_add_u32 s6, s6, s8
	s_addc_u32 s7, s7, s9
	s_add_u32 s10, s10, s18
	s_addc_u32 s11, s11, s19
	s_cmpk_lt_i32 s29, 0x100
	s_waitcnt vmcnt(0)
	v_mul_f32_e32 v9, v11, v11
	v_pk_mul_f32 v[36:37], v[12:13], v[12:13]
	v_fmac_f32_e32 v9, v10, v10
	v_add_f32_e32 v9, v9, v36
	v_pk_mul_f32 v[40:41], v[14:15], v[14:15]
	v_add_f32_e32 v9, v9, v37
	v_add_f32_e32 v9, v9, v40
	v_pk_mul_f32 v[38:39], v[16:17], v[16:17]
	v_add_f32_e32 v9, v9, v41
	v_add_f32_e32 v9, v9, v38
	v_add_f32_e32 v9, v9, v39
	s_waitcnt lgkmcnt(0)
	s_nop 0
	v_add_f32_dpp v9, v9, v9 quad_perm:[1,0,3,2] row_mask:0xf bank_mask:0xf
	s_waitcnt lgkmcnt(0)
	s_nop 0
	v_add_f32_dpp v9, v9, v9 quad_perm:[2,3,0,1] row_mask:0xf bank_mask:0xf
	s_waitcnt lgkmcnt(0)
	s_nop 0
	v_add_f32_dpp v9, v9, v9 row_half_mirror row_mask:0xf bank_mask:0xf
	s_waitcnt lgkmcnt(0)
	s_nop 0
	v_add_f32_dpp v9, v9, v9 row_mirror row_mask:0xf bank_mask:0xf
	v_fmamk_f32 v9, v9, 0x3c000000, v8
	v_mul_f32_e32 v36, 0x4b800000, v9
	v_cmp_gt_f32_e32 vcc, s13, v9
	s_nop 1
	v_cndmask_b32_e32 v9, v9, v36, vcc
	v_rsq_f32_e32 v9, v9
	s_nop 0
	v_mul_f32_e32 v36, 0x45800000, v9
	v_cndmask_b32_e32 v36, v9, v36, vcc
	v_pk_mul_f32 v[10:11], v[36:37], v[10:11] op_sel_hi:[0,1]
	v_pk_mul_f32 v[12:13], v[36:37], v[12:13] op_sel_hi:[0,1]
	v_pk_mul_f32 v[14:15], v[36:37], v[14:15] op_sel_hi:[0,1]
	v_pk_mul_f32 v[16:17], v[36:37], v[16:17] op_sel_hi:[0,1]
	v_pk_mul_f32 v[10:11], v[10:11], v[18:19]
	v_pk_mul_f32 v[12:13], v[12:13], v[20:21]
	v_pk_mul_f32 v[14:15], v[14:15], v[22:23]
	v_pk_mul_f32 v[16:17], v[16:17], v[24:25]
	global_store_dwordx4 v[34:35], v[10:13], off
	global_store_dwordx4 v[34:35], v[14:17], off offset:16
	v_add_co_u32_e32 v18, vcc, s28, v28
	v_cvt_pk_bf16_f32 v10, v10, v11
	v_cvt_pk_bf16_f32 v11, v12, v13
	v_cvt_pk_bf16_f32 v12, v14, v15
	v_cvt_pk_bf16_f32 v13, v16, v17
	global_store_dwordx4 v[32:33], v[10:13], off
	s_nop 0
	global_load_dwordx4 v[10:13], v[30:31], off offset:2048
	s_nop 0
	global_load_dwordx4 v[14:17], v[26:27], off offset:16
	v_addc_co_u32_e32 v19, vcc, 0, v29, vcc
	s_waitcnt vmcnt(1)
	global_store_dwordx4 v[18:19], v[10:13], off
	s_waitcnt vmcnt(1)
	global_store_dwordx4 v[18:19], v[14:17], off offset:16
	v_cvt_pk_bf16_f32 v10, v10, v11
	v_cvt_pk_bf16_f32 v11, v12, v13
	v_cvt_pk_bf16_f32 v12, v14, v15
	v_cvt_pk_bf16_f32 v13, v16, v17
	global_store_dwordx4 v[2:3], v[10:13], off
	v_lshl_add_u64 v[2:3], v[2:3], 0, s[4:5]
	s_cbranch_scc1 .LBB0_335
